# attn: drop load clamp so the last two tile loads of an item fetch the next item's tiles 0/1 (same head, next batch); following items skip bias-table, tile-0 load/LDS write and tile-1 load
# speedup vs baseline: 1.0164x; 1.0061x over previous
.LBB0_246:
	v_readlane_b32 s0, v255, 17
	s_cmpk_gt_i32 s0, 0x7ff
	s_movk_i32 s28, 0x101
	s_cbranch_scc1 .LBB0_262
	s_mov_b32 s32, 0
	s_waitcnt vmcnt(4)
	v_and_b32_e32 v1, 64, v185
	v_xor_b32_e32 v0, 16, v185
	v_add_u32_e32 v1, 64, v1
	v_cmp_lt_i32_e32 vcc, v0, v1
	s_add_u32 s4, s70, 0x9100000
	v_readlane_b32 s0, v255, 18
	v_cndmask_b32_e32 v0, v185, v0, vcc
	v_lshlrev_b32_e32 v159, 2, v0
	v_xor_b32_e32 v0, 32, v185
	s_addc_u32 s5, s71, 0
	s_lshl_b32 s2, s0, 4
	v_cmp_lt_i32_e32 vcc, v0, v1
	s_add_u32 s6, s70, 0x39900000
	v_readlane_b32 s12, v255, 17
	v_cndmask_b32_e32 v0, v185, v0, vcc
	v_lshlrev_b32_e32 v160, 2, v0
	s_addc_u32 s7, s71, 0
	s_sub_i32 s3, 64, s2
	s_lshl_b32 s10, s12, 7
	s_waitcnt lgkmcnt(0)
	s_lshl_b32 s11, s42, 7
	s_branch .LBB0_249

.LBB0_249:
	s_nop 0
	v_mov_b32_e32 v0, v65
	s_bfe_u32 s19, s12, 0x30005
	s_waitcnt vmcnt(19)
	v_add_u32_e32 v100, v0, v190
	v_cmp_gt_i32_e32 vcc, s28, v100
	s_barrier
	s_cmp_lg_u32 s32, 0
	s_cbranch_scc0 .Lch_full0
	s_mov_b64 s[8:9], exec
	s_branch .LBB0_251
.Lch_full0:
	s_and_saveexec_b64 s[8:9], vcc
	s_cbranch_execz .LBB0_251
	s_movk_i32 s0, 0x80
	v_add_u32_e32 v0, 0xffffff80, v100
	v_sub_u32_e32 v1, 0x80, v100
	v_cmp_gt_i32_e32 vcc, s0, v100
	s_mov_b32 s13, 0x40317218
	v_readlane_b32 s52, v252, 25
	v_cndmask_b32_e32 v0, v0, v1, vcc
	v_max_i32_e32 v1, 1, v0
	v_cvt_f32_u32_e32 v1, v1
	v_readlane_b32 s60, v252, 33
	v_readlane_b32 s61, v252, 34
	v_readlane_b32 s53, v252, 26
	v_mul_f32_e32 v1, 0x3e000000, v1
	v_cmp_gt_f32_e32 vcc, s92, v1
	v_readlane_b32 s54, v252, 27
	v_readlane_b32 s55, v252, 28
	v_cndmask_b32_e64 v2, 0, 32, vcc
	v_ldexp_f32 v1, v1, v2
	v_log_f32_e32 v1, v1
	v_cndmask_b32_e32 v2, 0, v187, vcc
	v_readlane_b32 s56, v252, 29
	v_readlane_b32 s57, v252, 30
	v_mul_f32_e32 v3, 0x3f317217, v1
	v_fma_f32 v3, v1, s41, -v3
	v_fmac_f32_e32 v3, 0x3377d1cf, v1
	v_fmac_f32_e32 v3, 0x3f317217, v1
	v_cmp_lt_f32_e64 vcc, |v1|, s68
	v_readlane_b32 s58, v252, 31
	v_readlane_b32 s59, v252, 32
	v_cndmask_b32_e32 v1, v1, v3, vcc
	v_sub_f32_e32 v1, v1, v2
	v_div_scale_f32 v2, s[14:15], s13, s13, v1
	v_rcp_f32_e32 v3, v2
	s_waitcnt vmcnt(3)
	v_div_scale_f32 v4, vcc, v1, s13, v1
	v_readlane_b32 s62, v252, 35
	v_fma_f32 v5, -v2, v3, 1.0
	v_fmac_f32_e32 v3, v5, v3
	v_mul_f32_e32 v5, v4, v3
	v_fma_f32 v6, -v2, v5, v4
	v_fmac_f32_e32 v5, v6, v3
	v_fma_f32 v2, -v2, v5, v4
	v_div_fmas_f32 v2, v2, v3, v5
	v_div_fixup_f32 v1, v2, s13, v1
	v_mul_f32_e32 v1, 0x41000000, v1
	v_cvt_i32_f32_e32 v1, v1
	v_cmp_lt_i32_e32 vcc, s0, v100
	v_readlane_b32 s63, v252, 36
	v_readlane_b32 s64, v252, 37
	v_min_i32_e32 v1, 7, v1
	v_cndmask_b32_e64 v2, 0, 16, vcc
	v_add_u32_e32 v1, 8, v1
	v_cmp_gt_i32_e32 vcc, 8, v0
	v_readlane_b32 s65, v252, 38
	v_readlane_b32 s66, v252, 39
	v_cndmask_b32_e32 v0, v1, v0, vcc
	v_add_u32_e32 v0, v0, v2
	v_lshl_or_b32 v0, v0, 3, s19
	v_ashrrev_i32_e32 v1, 31, v0
	v_lshl_add_u64 v[0:1], v[0:1], 2, s[60:61]
	global_load_dword v0, v[0:1], off
	v_lshl_add_u32 v1, v100, 2, 0
	v_add_u32_e32 v1, 0x1a800, v1
	v_readlane_b32 s67, v252, 40
	s_waitcnt vmcnt(0)
	v_mul_f32_e32 v0, 0x413504f3, v0
	ds_write_b32 v1, v0
.LBB0_251:
	s_or_b64 exec, exec, s[8:9]
	s_and_b32 s0, s10, 0x780
	s_sub_i32 s17, s3, s0
	s_lshl_b32 s0, s12, 3
	s_and_b32 s15, s0, 0xfffff800
	s_bfe_u32 s14, s12, 0x10004
	s_ashr_i32 s16, s15, 31
	s_mul_i32 s8, s15, 0xa080
	s_mul_hi_i32 s0, s15, 0xa080
	s_add_u32 s9, s4, s8
	s_addc_u32 s18, s5, s0
	s_lshl_b32 s13, s19, 8
	s_lshl_b32 s0, s19, 9
	s_lshl_b32 s8, s14, 8
	s_add_u32 s20, s9, s0
	s_addc_u32 s21, s18, 0
	s_add_u32 s22, s20, s8
	v_lshlrev_b32_e32 v0, 4, v100
	s_addc_u32 s23, s21, 0
	s_add_u32 s24, s22, 0x7000
	s_addc_u32 s25, s23, 0
	s_add_u32 s26, s20, 0x8000
	s_addc_u32 s27, s21, 0
	v_and_b32_e32 v26, 0xf0, v0
	v_mov_b32_e32 v27, v65
	v_lshl_add_u64 v[0:1], s[22:23], 0, v[26:27]
	s_mov_b64 s[22:23], 0x7000
	v_lshl_add_u64 v[154:155], v[0:1], 0, s[22:23]
	v_ashrrev_i32_e32 v161, 4, v100
	v_add_u32_e32 v27, 0x200, v100
	v_mad_i64_i32 v[0:1], s[22:23], v161, s69, v[154:155]
	v_ashrrev_i32_e32 v162, 4, v27
	v_mad_i64_i32 v[2:3], s[22:23], v162, s69, v[154:155]
	v_and_b32_e32 v246, 15, v190
	v_mul_u32_u24_e32 v247, 0xa080, v161
	v_lshl_add_u32 v246, v246, 4, v247
	v_add_u32_e32 v247, 0x141000, v246
	v_lshrrev_b32_e32 v239, 5, v190
	v_and_b32_e32 v169, 7, v239
	v_lshlrev_b32_e32 v169, 1, v169
	v_and_b32_e32 v172, 31, v190
	v_xor_b32_e32 v169, v169, v172
	v_mul_u32_u24_e32 v239, 0xa080, v239
	v_lshl_add_u32 v239, v169, 4, v239
	v_lshlrev_b32_e32 v169, 4, v190
	v_add_u32_e32 v169, 0x8800, v169
	v_lshrrev_b32_e32 v171, 2, v185
	v_and_b32_e32 v220, 3, v185
	v_lshlrev_b32_e32 v220, 3, v220
	v_lshl_add_u32 v220, v171, 9, v220
	v_add_u32_e32 v220, 0x8800, v220
	v_and_b32_e32 v171, 7, v171
	v_xor_b32_e32 v172, 0, v171
	v_lshl_add_u32 v172, v172, 5, v220
	v_xor_b32_e32 v175, 1, v171
	v_lshl_add_u32 v175, v175, 5, v220
	v_xor_b32_e32 v176, 2, v171
	v_lshl_add_u32 v176, v176, 5, v220
	v_xor_b32_e32 v181, 3, v171
	v_lshl_add_u32 v181, v181, 5, v220
	v_xor_b32_e32 v218, 4, v171
	v_lshl_add_u32 v218, v218, 5, v220
	v_xor_b32_e32 v219, 5, v171
	v_lshl_add_u32 v219, v219, 5, v220
	v_xor_b32_e32 v27, 7, v171
	v_xor_b32_e32 v171, 6, v171
	v_lshl_add_u32 v171, v171, 5, v220
	v_lshl_add_u32 v27, v27, 5, v220
	v_mov_b32_e32 v220, v171
	v_mov_b32_e32 v171, v27
	s_cmp_lg_u32 s32, 0
	s_cbranch_scc1 .Lch_skipB
	global_load_dwordx4 v[18:21], v[0:1], off
	global_load_dwordx4 v[22:25], v[2:3], off
	s_mov_b32 s29, 0x0
	s_add_u32 s72, s24, s29
	s_addc_u32 s73, s25, 0
	s_add_u32 s74, s26, s29
	s_addc_u32 s75, s27, 0
	s_add_u32 s76, s74, 0xa0800
	s_addc_u32 s77, s75, 0
	s_add_u32 s78, s76, 0xa0800
	s_addc_u32 s79, s77, 0
	s_add_u32 s80, s78, 0xa0800
	s_addc_u32 s81, s79, 0
	s_waitcnt vmcnt(2)
	global_load_dwordx4 v[206:209], v239, s[74:75]
	global_load_dwordx4 v[210:213], v239, s[76:77]
	global_load_dwordx4 v[214:217], v239, s[78:79]
	global_load_dwordx4 v[248:251], v239, s[80:81]
.Lch_skipB:
	s_lshl_b32 s18, s12, 7
	s_and_b32 s18, s18, 0x780
	s_add_i32 s18, s18, s2
	s_lshl_b32 s19, s19, 2
	v_readlane_b32 s52, v252, 25
	v_and_b32_e32 v165, 15, v100
	v_readlane_b32 s60, v252, 33
	v_readlane_b32 s61, v252, 34
	s_mov_b32 s9, s1
	v_bfe_u32 v43, v100, 4, 2
	v_lshlrev_b32_e32 v64, 4, v43
	v_add_u32_e32 v26, 0, v26
	v_lshlrev_b32_e32 v158, 3, v43
	v_mov_b32_e32 v0, s19
	s_add_i32 s19, s18, s15
	global_load_dword v44, v0, s[60:61] offset:480
	global_load_dword v45, v0, s[60:61] offset:992
	v_or_b32_e32 v2, s19, v165
	v_mov_b64_e32 v[0:1], s[4:5]
	v_mad_i64_i32 v[0:1], s[20:21], v2, s69, v[0:1]
	v_lshl_add_u64 v[0:1], v[0:1], 0, s[0:1]
	v_lshl_add_u64 v[0:1], v[0:1], 0, s[8:9]
	v_lshl_add_u64 v[0:1], v[0:1], 0, v[64:65]
	s_movk_i32 s0, 0x6000
	v_add_co_u32_e32 v8, vcc, s0, v0
	s_movk_i32 s0, 0x110
	s_mov_b64 s[8:9], 0x6000
	v_mul_lo_u32 v46, v161, s0
	v_lshl_add_u64 v[12:13], v[0:1], 0, s[8:9]
	v_addc_co_u32_e32 v9, vcc, 0, v1, vcc
	v_add_u32_e32 v166, v26, v46
	global_load_dwordx4 v[0:3], v[12:13], off offset:64
	global_load_dwordx4 v[4:7], v[12:13], off offset:128
	s_nop 0
	global_load_dwordx4 v[8:11], v[8:9], off
	s_nop 0
	global_load_dwordx4 v[12:15], v[12:13], off offset:192
	s_waitcnt vmcnt(0)
	s_cmp_lg_u32 s32, 0
	s_cbranch_scc1 .Lch_c1
	ds_write_b128 v166, v[18:21]
.Lch_c1:
	v_mul_lo_u32 v101, v162, s0
	v_add_u32_e32 v167, v26, v101
	s_waitcnt vmcnt(22)
	s_cmp_lg_u32 s32, 0
	s_cbranch_scc1 .Lch_c2
	ds_write_b128 v167, v[22:25]
.Lch_c2:
	s_cmp_lg_u32 0, -1
	v_mov_b32_e32 v66, v65
	v_mov_b32_e32 v67, v65
	v_mov_b32_e32 v221, 0xf149f2ca
	v_mov_b32_e32 v222, 0
	v_readlane_b32 s53, v252, 26
	v_readlane_b32 s54, v252, 27
	v_readlane_b32 s55, v252, 28
	s_cmp_lg_u32 s32, 0
	s_cbranch_scc1 .Lch_c3
	ds_write_b128 v169, v[206:209] offset:0
	ds_write_b128 v169, v[210:213] offset:8192
	ds_write_b128 v169, v[214:217] offset:16384
	ds_write_b128 v169, v[248:251] offset:24576
	s_waitcnt lgkmcnt(0)
	s_barrier
	s_mov_b32 s29, 0x282000
	s_add_u32 s72, s24, s29
	s_addc_u32 s73, s25, 0
	s_add_u32 s74, s26, s29
	s_addc_u32 s75, s27, 0
	s_add_u32 s76, s74, 0xa0800
	s_addc_u32 s77, s75, 0
	s_add_u32 s78, s76, 0xa0800
	s_addc_u32 s79, s77, 0
	s_add_u32 s80, s78, 0xa0800
	s_addc_u32 s81, s79, 0
	global_load_dwordx4 v[194:197], v239, s[74:75]
	global_load_dwordx4 v[198:201], v239, s[76:77]
	global_load_dwordx4 v[202:205], v239, s[78:79]
	global_load_dwordx4 v[242:245], v239, s[80:81]
	global_load_dwordx4 v[16:19], v246, s[72:73]
	global_load_dwordx4 v[20:23], v247, s[72:73]
.Lch_c3:
	v_readlane_b32 s8, v254, 60
	s_waitcnt vmcnt(15)
	v_mul_f32_e32 v173, 0x413504f3, v44
	s_waitcnt vmcnt(14)
	v_mul_f32_e32 v174, 0x413504f3, v45
	v_readlane_b32 s56, v252, 29
	v_readlane_b32 s57, v252, 30
	v_readlane_b32 s58, v252, 31
	v_readlane_b32 s59, v252, 32
	v_mad_u32_u24 v27, v165, s0, v64
	s_cselect_b32 s0, 0, 0
	s_cmp_lg_u32 s8, -1
	s_cselect_b32 s8, s8, 0
	v_mov_b32_e32 v64, v65
	v_lshlrev_b32_e32 v30, 2, v43
	v_add_u32_e32 v177, s0, v27
	s_add_i32 s8, s0, 0x4400
	s_add_i32 s0, s0, 0x11800
	v_mov_b64_e32 v[36:37], v[64:65]
	v_mov_b64_e32 v[44:45], v[64:65]
	v_mov_b64_e32 v[52:53], v[64:65]
	v_mov_b64_e32 v[60:61], v[64:65]
	v_mov_b64_e32 v[70:71], v[66:67]
	v_mov_b64_e32 v[78:79], v[66:67]
	v_mov_b64_e32 v[86:87], v[66:67]
	v_mov_b64_e32 v[94:95], v[66:67]
	v_mov_b64_e32 v[32:33], v[64:65]
	v_mov_b64_e32 v[40:41], v[64:65]
	v_mov_b64_e32 v[48:49], v[64:65]
	v_mov_b64_e32 v[56:57], v[64:65]
	v_mov_b64_e32 v[74:75], v[66:67]
	v_mov_b64_e32 v[82:83], v[66:67]
	v_mov_b64_e32 v[90:91], v[66:67]
	v_mov_b64_e32 v[98:99], v[66:67]
	s_mov_b32 s29, 0x504000
	s_add_u32 s72, s24, s29
	s_addc_u32 s73, s25, 0
	s_add_u32 s74, s26, s29
	s_addc_u32 s75, s27, 0
	s_add_u32 s76, s74, 0xa0800
	s_addc_u32 s77, s75, 0
	s_add_u32 s78, s76, 0xa0800
	s_addc_u32 s79, s77, 0
	s_add_u32 s80, s78, 0xa0800
	s_addc_u32 s81, s79, 0
	s_mov_b32 s32, 1
	v_add_u32_e32 v191, s8, v27
	v_sub_u32_e32 v193, v30, v165
	s_mov_b32 s0, -2
	v_mov_b64_e32 v[38:39], v[66:67]
	v_mov_b64_e32 v[46:47], v[66:67]
	v_mov_b64_e32 v[54:55], v[66:67]
	v_mov_b64_e32 v[62:63], v[66:67]
	v_mov_b64_e32 v[68:69], v[64:65]
	v_mov_b64_e32 v[76:77], v[64:65]
	v_mov_b64_e32 v[84:85], v[64:65]
	v_mov_b64_e32 v[92:93], v[64:65]
	v_mov_b64_e32 v[34:35], v[66:67]
	v_mov_b64_e32 v[42:43], v[66:67]
	v_mov_b64_e32 v[50:51], v[66:67]
	v_mov_b64_e32 v[58:59], v[66:67]
	v_mov_b64_e32 v[72:73], v[64:65]
	v_mov_b64_e32 v[80:81], v[64:65]
	v_mov_b64_e32 v[88:89], v[64:65]
	v_mov_b64_e32 v[96:97], v[64:65]
	v_readlane_b32 s62, v252, 35
	v_readlane_b32 s63, v252, 36
	v_readlane_b32 s64, v252, 37
	v_readlane_b32 s65, v252, 38
	v_readlane_b32 s66, v252, 39
	v_readlane_b32 s67, v252, 40

.LBB0_256:
	v_sub_f32_e32 v66, v66, v221
	v_mul_f32_e32 v66, 0x3e0293ee, v66
	v_fmamk_f32 v67, v104, 0x3e0293ee, v66
	v_exp_f32_e32 v223, v67
	v_fmamk_f32 v67, v105, 0x3e0293ee, v66
	v_exp_f32_e32 v224, v67
	v_fmamk_f32 v67, v106, 0x3e0293ee, v66
	v_exp_f32_e32 v225, v67
	v_fmamk_f32 v67, v107, 0x3e0293ee, v66
	v_exp_f32_e32 v226, v67
	v_fmamk_f32 v67, v100, 0x3e0293ee, v66
	v_exp_f32_e32 v227, v67
	v_fmamk_f32 v67, v101, 0x3e0293ee, v66
	v_exp_f32_e32 v228, v67
	v_fmamk_f32 v67, v102, 0x3e0293ee, v66
	v_exp_f32_e32 v229, v67
	v_fmamk_f32 v67, v103, 0x3e0293ee, v66
	v_exp_f32_e32 v230, v67
	v_fmamk_f32 v67, v128, 0x3e0293ee, v66
	v_exp_f32_e32 v231, v67
	v_fmamk_f32 v67, v129, 0x3e0293ee, v66
	v_exp_f32_e32 v232, v67
	v_fmamk_f32 v67, v130, 0x3e0293ee, v66
	v_exp_f32_e32 v233, v67
	v_fmamk_f32 v67, v131, 0x3e0293ee, v66
	v_exp_f32_e32 v234, v67
	v_fmamk_f32 v67, v112, 0x3e0293ee, v66
	v_exp_f32_e32 v235, v67
	v_fmamk_f32 v67, v113, 0x3e0293ee, v66
	v_exp_f32_e32 v236, v67
	v_fmamk_f32 v67, v114, 0x3e0293ee, v66
	v_fmac_f32_e32 v66, 0x3e0293ee, v115
	v_exp_f32_e32 v237, v67
	v_exp_f32_e32 v238, v66
	s_waitcnt lgkmcnt(0)
	s_add_i32 s8, s0, 2
	v_cvt_pk_bf16_f32 v104, v223, v224
	v_cvt_pk_bf16_f32 v105, v225, v226
	v_cvt_pk_bf16_f32 v106, v227, v228
	v_cvt_pk_bf16_f32 v107, v229, v230
	v_cvt_pk_bf16_f32 v100, v231, v232
	v_cvt_pk_bf16_f32 v101, v233, v234
	v_cvt_pk_bf16_f32 v102, v235, v236
	v_cvt_pk_bf16_f32 v103, v237, v238
	v_mfma_f32_16x16x32_bf16 v[96:99], v[116:119], v[104:107], v[96:99]
	s_nop 0
	v_mfma_f32_16x16x32_bf16 v[96:99], v[108:111], v[100:103], v[96:99]
	ds_read_b64_tr_b16 v[108:109], v218 offset:0
	ds_read_b64_tr_b16 v[110:111], v218 offset:8192
	ds_read_b64_tr_b16 v[112:113], v218 offset:16384
	ds_read_b64_tr_b16 v[114:115], v218 offset:24576
	v_mfma_f32_16x16x32_bf16 v[88:91], v[120:123], v[104:107], v[88:91]
	ds_read_b64_tr_b16 v[116:117], v219 offset:0
	ds_read_b64_tr_b16 v[118:119], v219 offset:8192
	ds_read_b64_tr_b16 v[120:121], v219 offset:16384
	ds_read_b64_tr_b16 v[122:123], v219 offset:24576
	v_mfma_f32_16x16x32_bf16 v[80:83], v[136:139], v[104:107], v[80:83]
	v_mfma_f32_16x16x32_bf16 v[88:91], v[124:127], v[100:103], v[88:91]
	ds_read_b64_tr_b16 v[124:125], v220 offset:0
	ds_read_b64_tr_b16 v[126:127], v220 offset:8192
	ds_read_b64_tr_b16 v[128:129], v220 offset:16384
	v_mfma_f32_16x16x32_bf16 v[72:75], v[140:143], v[104:107], v[72:75]
	ds_read_b64_tr_b16 v[130:131], v220 offset:24576
	v_mfma_f32_16x16x32_bf16 v[80:83], v[132:135], v[100:103], v[80:83]
	ds_read_b64_tr_b16 v[132:133], v171 offset:0
	ds_read_b64_tr_b16 v[134:135], v171 offset:8192
	ds_read_b64_tr_b16 v[136:137], v171 offset:16384
	v_mfma_f32_16x16x32_bf16 v[72:75], v[144:147], v[100:103], v[72:75]
	ds_read_b64_tr_b16 v[138:139], v171 offset:24576
	s_waitcnt lgkmcnt(0)
	v_mfma_f32_16x16x32_bf16 v[56:59], v[108:111], v[104:107], v[56:59]
	ds_read_b64_tr_b16 v[108:109], v172 offset:256
	ds_read_b64_tr_b16 v[110:111], v172 offset:8448
	v_mfma_f32_16x16x32_bf16 v[48:51], v[116:119], v[104:107], v[48:51]
	v_mfma_f32_16x16x32_bf16 v[56:59], v[112:115], v[100:103], v[56:59]
	ds_read_b64_tr_b16 v[112:113], v172 offset:16640
	ds_read_b64_tr_b16 v[114:115], v172 offset:24832
	ds_read_b64_tr_b16 v[116:117], v175 offset:256
	ds_read_b64_tr_b16 v[118:119], v175 offset:8448
	v_mfma_f32_16x16x32_bf16 v[40:43], v[124:127], v[104:107], v[40:43]
	v_mfma_f32_16x16x32_bf16 v[48:51], v[120:123], v[100:103], v[48:51]
	ds_read_b64_tr_b16 v[120:121], v175 offset:16640
	ds_read_b64_tr_b16 v[122:123], v175 offset:24832
	ds_read_b64_tr_b16 v[124:125], v176 offset:256
	ds_read_b64_tr_b16 v[126:127], v176 offset:8448
	v_mfma_f32_16x16x32_bf16 v[32:35], v[132:135], v[104:107], v[32:35]
	v_mfma_f32_16x16x32_bf16 v[40:43], v[128:131], v[100:103], v[40:43]
	ds_read_b64_tr_b16 v[128:129], v176 offset:16640
	ds_read_b64_tr_b16 v[130:131], v176 offset:24832
	ds_read_b64_tr_b16 v[132:133], v181 offset:256
	ds_read_b64_tr_b16 v[134:135], v181 offset:8448
	v_mfma_f32_16x16x32_bf16 v[32:35], v[136:139], v[100:103], v[32:35]
	ds_read_b64_tr_b16 v[136:137], v181 offset:16640
	ds_read_b64_tr_b16 v[138:139], v181 offset:24832
	s_waitcnt lgkmcnt(0)
	v_mfma_f32_16x16x32_bf16 v[92:95], v[108:111], v[104:107], v[92:95]
	ds_read_b64_tr_b16 v[108:109], v218 offset:256
	ds_read_b64_tr_b16 v[110:111], v218 offset:8448
	v_mfma_f32_16x16x32_bf16 v[84:87], v[116:119], v[104:107], v[84:87]
	v_mfma_f32_16x16x32_bf16 v[92:95], v[112:115], v[100:103], v[92:95]
	ds_read_b64_tr_b16 v[112:113], v218 offset:16640
	ds_read_b64_tr_b16 v[114:115], v218 offset:24832
	ds_read_b64_tr_b16 v[116:117], v219 offset:256
	ds_read_b64_tr_b16 v[118:119], v219 offset:8448
	v_mfma_f32_16x16x32_bf16 v[76:79], v[124:127], v[104:107], v[76:79]
	v_mfma_f32_16x16x32_bf16 v[84:87], v[120:123], v[100:103], v[84:87]
	ds_read_b64_tr_b16 v[120:121], v219 offset:16640
	ds_read_b64_tr_b16 v[122:123], v219 offset:24832
	ds_read_b64_tr_b16 v[124:125], v220 offset:256
	ds_read_b64_tr_b16 v[126:127], v220 offset:8448
	v_mfma_f32_16x16x32_bf16 v[66:69], v[132:135], v[104:107], v[68:71]
	v_mfma_f32_16x16x32_bf16 v[76:79], v[128:131], v[100:103], v[76:79]
	ds_read_b64_tr_b16 v[128:129], v220 offset:16640
	ds_read_b64_tr_b16 v[130:131], v220 offset:24832
	ds_read_b64_tr_b16 v[132:133], v171 offset:256
	ds_read_b64_tr_b16 v[134:135], v171 offset:8448
	v_mfma_f32_16x16x32_bf16 v[66:69], v[136:139], v[100:103], v[66:69]
	ds_read_b64_tr_b16 v[136:137], v171 offset:16640
	ds_read_b64_tr_b16 v[138:139], v171 offset:24832
	s_waitcnt lgkmcnt(0)
	v_mfma_f32_16x16x32_bf16 v[60:63], v[108:111], v[104:107], v[60:63]
	s_waitcnt vmcnt(6)
	ds_write_b128 v166, v[16:19] offset:17408
	v_mfma_f32_16x16x32_bf16 v[52:55], v[116:119], v[104:107], v[52:55]
	ds_write_b128 v167, v[20:23] offset:17408
	v_mfma_f32_16x16x32_bf16 v[44:47], v[124:127], v[104:107], v[44:47]
	ds_write_b128 v169, v[194:197] offset:36864
	v_mfma_f32_16x16x32_bf16 v[36:39], v[132:135], v[104:107], v[36:39]
	ds_write_b128 v169, v[198:201] offset:45056
	v_mfma_f32_16x16x32_bf16 v[60:63], v[112:115], v[100:103], v[60:63]
	ds_write_b128 v169, v[202:205] offset:53248
	v_mfma_f32_16x16x32_bf16 v[52:55], v[120:123], v[100:103], v[52:55]
	ds_write_b128 v169, v[242:245] offset:61440
	v_mfma_f32_16x16x32_bf16 v[44:47], v[128:131], v[100:103], v[44:47]
	v_mfma_f32_16x16x32_bf16 v[36:39], v[136:139], v[100:103], v[36:39]
	s_mov_b32 s9, s8
	s_lshl_b32 s9, s9, 6
	s_addk_i32 s9, 0xc0
	s_mul_i32 s29, s9, 0xa080
	s_add_u32 s72, s24, s29
	s_addc_u32 s73, s25, 0
	s_add_u32 s74, s26, s29
	s_addc_u32 s75, s27, 0
	s_add_u32 s76, s74, 0xa0800
	s_addc_u32 s77, s75, 0
	s_add_u32 s78, s76, 0xa0800
	s_addc_u32 s79, s77, 0
	s_add_u32 s80, s78, 0xa0800
	s_addc_u32 s81, s79, 0
	s_waitcnt lgkmcnt(0)
	s_barrier
	ds_read_b128 v[100:103], v191 offset:0
	ds_read_b128 v[104:107], v191 offset:64
	ds_read_b128 v[108:111], v191 offset:0x80
	ds_read_b128 v[112:115], v191 offset:0xc0
	ds_read_b128 v[116:119], v191 offset:0x1100
	ds_read_b128 v[120:123], v191 offset:0x1140
	ds_read_b128 v[124:127], v191 offset:0x1180
	ds_read_b128 v[128:131], v191 offset:0x11c0
	global_load_dwordx4 v[194:197], v239, s[74:75]
	global_load_dwordx4 v[198:201], v239, s[76:77]
	global_load_dwordx4 v[202:205], v239, s[78:79]
	global_load_dwordx4 v[242:245], v239, s[80:81]
	global_load_dwordx4 v[16:19], v246, s[72:73]
	global_load_dwordx4 v[20:23], v247, s[72:73]
	s_waitcnt lgkmcnt(0)
	s_nop 0
	v_mfma_f32_16x16x32_bf16 v[100:103], v[100:103], v[8:11], 0
	v_mfma_f32_16x16x32_bf16 v[116:119], v[116:119], v[8:11], 0
	v_mfma_f32_16x16x32_bf16 v[100:103], v[104:107], v[0:3], v[100:103]
	v_mfma_f32_16x16x32_bf16 v[104:107], v[120:123], v[0:3], v[116:119]
	v_mfma_f32_16x16x32_bf16 v[100:103], v[108:111], v[4:7], v[100:103]
	v_mfma_f32_16x16x32_bf16 v[104:107], v[124:127], v[4:7], v[104:107]
	v_mfma_f32_16x16x32_bf16 v[112:115], v[112:115], v[12:15], v[100:103]
	v_mfma_f32_16x16x32_bf16 v[100:103], v[128:131], v[12:15], v[104:107]
	ds_read_b128 v[104:107], v191 offset:0x2200
	ds_read_b128 v[108:111], v191 offset:0x2240
	ds_read_b128 v[116:119], v191 offset:0x2280
	ds_read_b128 v[120:123], v191 offset:0x22c0
	ds_read_b128 v[124:127], v191 offset:0x3300
	ds_read_b128 v[128:131], v191 offset:0x3340
	ds_read_b128 v[132:135], v191 offset:0x3380
	ds_read_b128 v[136:139], v191 offset:0x33c0
	s_waitcnt lgkmcnt(0)
	s_nop 5
	v_mfma_f32_16x16x32_bf16 v[104:107], v[104:107], v[8:11], 0
	s_add_i32 s9, s17, 0xffffff96
	s_cmp_lt_u32 s9, 0xfffffefd
	v_mfma_f32_16x16x32_bf16 v[104:107], v[108:111], v[0:3], v[104:107]
	v_mfma_f32_16x16x32_bf16 v[124:127], v[124:127], v[8:11], 0
	v_mfma_f32_16x16x32_bf16 v[104:107], v[116:119], v[4:7], v[104:107]
	ds_read_b64_tr_b16 v[116:117], v172 offset:36864
	ds_read_b64_tr_b16 v[118:119], v172 offset:45056
	v_mfma_f32_16x16x32_bf16 v[108:111], v[128:131], v[0:3], v[124:127]
	v_mfma_f32_16x16x32_bf16 v[128:131], v[120:123], v[12:15], v[104:107]
	ds_read_b64_tr_b16 v[104:105], v172 offset:53248
	ds_read_b64_tr_b16 v[106:107], v172 offset:61440
	ds_read_b64_tr_b16 v[120:121], v175 offset:36864
	v_mfma_f32_16x16x32_bf16 v[108:111], v[132:135], v[4:7], v[108:111]
	ds_read_b64_tr_b16 v[122:123], v175 offset:45056
	ds_read_b64_tr_b16 v[124:125], v175 offset:53248
	ds_read_b64_tr_b16 v[126:127], v175 offset:61440
	v_mfma_f32_16x16x32_bf16 v[108:111], v[136:139], v[12:15], v[108:111]
	ds_read_b64_tr_b16 v[136:137], v176 offset:36864
	ds_read_b64_tr_b16 v[138:139], v176 offset:45056
	ds_read_b64_tr_b16 v[132:133], v176 offset:53248
	ds_read_b64_tr_b16 v[134:135], v176 offset:61440
	ds_read_b64_tr_b16 v[140:141], v181 offset:36864
	ds_read_b64_tr_b16 v[142:143], v181 offset:45056
	ds_read_b64_tr_b16 v[144:145], v181 offset:53248
	ds_read_b64_tr_b16 v[146:147], v181 offset:61440
	s_cbranch_scc1 .LBB0_258
	v_add_u32_e32 v70, s17, v193
	v_add_u32_e32 v152, 0x80, v70
	v_max_i32_e32 v71, -1, v152
	v_add_u32_e32 v71, 1, v71
	v_med3_i32 v70, v152, 0, v188
	s_add_i32 s9, 0, 0x1a800
	v_min_u32_e32 v71, 0x100, v71
	v_lshl_add_u32 v70, v70, 2, s9
	v_lshl_add_u32 v71, v71, 2, s9
	ds_read_b32 v70, v70
	ds_read_b32 v71, v71
	v_max_i32_e32 v153, -2, v152
	v_add_u32_e32 v153, 2, v153
	v_min_u32_e32 v153, 0x100, v153
	v_lshl_add_u32 v153, v153, 2, s9
	ds_read_b32 v240, v153
	v_max_i32_e32 v153, -3, v152
	s_waitcnt lgkmcnt(1)
	v_pk_add_f32 v[112:113], v[112:113], v[70:71]
	v_max_i32_e32 v70, -16, v152
	v_max_i32_e32 v71, 0xffffffef, v152
	v_add_u32_e32 v153, 3, v153
	v_add_u32_e32 v70, 16, v70
	v_add_u32_e32 v71, 17, v71
	v_min_u32_e32 v153, 0x100, v153
	v_min_u32_e32 v70, 0x100, v70
	v_min_u32_e32 v71, 0x100, v71
	v_lshl_add_u32 v153, v153, 2, s9
	v_lshl_add_u32 v70, v70, 2, s9
	v_lshl_add_u32 v71, v71, 2, s9
	ds_read_b32 v241, v153
	ds_read_b32 v70, v70
	ds_read_b32 v71, v71
	v_max_i32_e32 v153, 0xffffffee, v152
	v_add_u32_e32 v153, 18, v153
	v_min_u32_e32 v153, 0x100, v153
	v_lshl_add_u32 v153, v153, 2, s9
	s_waitcnt lgkmcnt(0)
	v_pk_add_f32 v[100:101], v[100:101], v[70:71]
	v_max_i32_e32 v70, 0xffffffe0, v152
	v_max_i32_e32 v71, 0xffffffdf, v152
	v_add_u32_e32 v70, 32, v70
	v_add_u32_e32 v71, 33, v71
	v_min_u32_e32 v70, 0x100, v70
	v_min_u32_e32 v71, 0x100, v71
	v_lshl_add_u32 v70, v70, 2, s9
	v_lshl_add_u32 v71, v71, 2, s9
	v_pk_add_f32 v[114:115], v[114:115], v[240:241]
	ds_read_b32 v240, v153
	ds_read_b32 v70, v70
	ds_read_b32 v71, v71
	v_max_i32_e32 v153, 0xffffffed, v152
	v_add_u32_e32 v153, 19, v153
	v_min_u32_e32 v153, 0x100, v153
	v_lshl_add_u32 v153, v153, 2, s9
	ds_read_b32 v241, v153
	v_max_i32_e32 v153, 0xffffffde, v152
	v_add_u32_e32 v153, 34, v153
	v_min_u32_e32 v153, 0x100, v153
	v_lshl_add_u32 v153, v153, 2, s9
	s_waitcnt lgkmcnt(0)
	v_pk_add_f32 v[102:103], v[102:103], v[240:241]
	ds_read_b32 v240, v153
	v_max_i32_e32 v153, 0xffffffdd, v152
	v_add_u32_e32 v153, 35, v153
	v_min_u32_e32 v153, 0x100, v153
	v_lshl_add_u32 v153, v153, 2, s9
	ds_read_b32 v241, v153
	v_pk_add_f32 v[128:129], v[128:129], v[70:71]
	v_max_i32_e32 v70, 0xffffffd0, v152
	v_max_i32_e32 v71, 0xffffffcf, v152
	v_max_i32_e32 v153, 0xffffffce, v152
	v_max_i32_e32 v152, 0xffffffcd, v152
	v_add_u32_e32 v70, 48, v70
	v_add_u32_e32 v71, 49, v71
	v_add_u32_e32 v153, 50, v153
	v_add_u32_e32 v152, 51, v152
	v_min_u32_e32 v70, 0x100, v70
	v_min_u32_e32 v71, 0x100, v71
	v_min_u32_e32 v153, 0x100, v153
	v_min_u32_e32 v152, 0x100, v152
	v_lshl_add_u32 v70, v70, 2, s9
	v_lshl_add_u32 v71, v71, 2, s9
	v_lshl_add_u32 v153, v153, 2, s9
	v_lshl_add_u32 v152, v152, 2, s9
	s_waitcnt lgkmcnt(0)
	v_pk_add_f32 v[130:131], v[130:131], v[240:241]
	ds_read_b32 v70, v70
	ds_read_b32 v71, v71
	ds_read_b32 v240, v153
	ds_read_b32 v241, v152
	s_waitcnt lgkmcnt(2)
	v_pk_add_f32 v[108:109], v[108:109], v[70:71]
	s_waitcnt lgkmcnt(0)
	v_pk_add_f32 v[110:111], v[110:111], v[240:241]

.LBB0_260:
	v_sub_f32_e32 v70, v70, v221
	v_mul_f32_e32 v70, 0x3e0293ee, v70
	v_fmamk_f32 v71, v112, 0x3e0293ee, v70
	v_exp_f32_e32 v71, v71
	v_fmamk_f32 v112, v113, 0x3e0293ee, v70
	v_exp_f32_e32 v112, v112
	v_fmamk_f32 v113, v114, 0x3e0293ee, v70
	v_exp_f32_e32 v113, v113
	v_fmamk_f32 v114, v115, 0x3e0293ee, v70
	v_exp_f32_e32 v114, v114
	v_fmamk_f32 v100, v100, 0x3e0293ee, v70
	v_add_f32_e32 v115, 0, v71
	v_exp_f32_e32 v100, v100
	v_fmamk_f32 v101, v101, 0x3e0293ee, v70
	v_add_f32_e32 v115, v112, v115
	v_exp_f32_e32 v101, v101
	v_fmamk_f32 v102, v102, 0x3e0293ee, v70
	v_add_f32_e32 v115, v113, v115
	v_exp_f32_e32 v102, v102
	v_fmamk_f32 v103, v103, 0x3e0293ee, v70
	v_add_f32_e32 v115, v114, v115
	v_exp_f32_e32 v103, v103
	v_fmamk_f32 v128, v128, 0x3e0293ee, v70
	v_add_f32_e32 v115, v100, v115
	v_exp_f32_e32 v128, v128
	v_fmamk_f32 v129, v129, 0x3e0293ee, v70
	v_fmamk_f32 v108, v108, 0x3e0293ee, v70
	v_add_f32_e32 v115, v101, v115
	v_exp_f32_e32 v129, v129
	v_fmamk_f32 v130, v130, 0x3e0293ee, v70
	v_exp_f32_e32 v153, v108
	v_fmamk_f32 v108, v109, 0x3e0293ee, v70
	v_add_f32_e32 v115, v102, v115
	v_exp_f32_e32 v130, v130
	v_fmamk_f32 v131, v131, 0x3e0293ee, v70
	v_exp_f32_e32 v223, v108
	v_fmamk_f32 v108, v110, 0x3e0293ee, v70
	v_fmac_f32_e32 v70, 0x3e0293ee, v111
	v_add_f32_e32 v115, v103, v115
	v_exp_f32_e32 v131, v131
	v_exp_f32_e32 v224, v108
	v_exp_f32_e32 v225, v70
	v_add_f32_e32 v115, v128, v115
	s_waitcnt lgkmcnt(0)
	v_add_f32_e32 v115, v129, v115
	v_add_f32_e32 v115, v130, v115
	s_add_i32 s0, s0, 3
	v_add_f32_e32 v152, v131, v115
	v_cvt_pk_bf16_f32 v108, v71, v112
	v_cvt_pk_bf16_f32 v109, v113, v114
	v_cvt_pk_bf16_f32 v110, v100, v101
	v_cvt_pk_bf16_f32 v111, v102, v103
	v_cvt_pk_bf16_f32 v100, v128, v129
	v_cvt_pk_bf16_f32 v101, v130, v131
	v_cvt_pk_bf16_f32 v102, v153, v223
	v_cvt_pk_bf16_f32 v103, v224, v225
	v_mfma_f32_16x16x32_bf16 v[96:99], v[116:119], v[108:111], v[96:99]
	s_nop 0
	v_mfma_f32_16x16x32_bf16 v[96:99], v[104:107], v[100:103], v[96:99]
	ds_read_b64_tr_b16 v[104:105], v218 offset:36864
	ds_read_b64_tr_b16 v[106:107], v218 offset:45056
	ds_read_b64_tr_b16 v[112:113], v218 offset:53248
	ds_read_b64_tr_b16 v[114:115], v218 offset:61440
	v_mfma_f32_16x16x32_bf16 v[88:91], v[120:123], v[108:111], v[88:91]
	ds_read_b64_tr_b16 v[116:117], v219 offset:36864
	ds_read_b64_tr_b16 v[118:119], v219 offset:45056
	ds_read_b64_tr_b16 v[120:121], v219 offset:53248
	ds_read_b64_tr_b16 v[122:123], v219 offset:61440
	v_mfma_f32_16x16x32_bf16 v[80:83], v[136:139], v[108:111], v[80:83]
	v_mfma_f32_16x16x32_bf16 v[88:91], v[124:127], v[100:103], v[88:91]
	ds_read_b64_tr_b16 v[124:125], v220 offset:36864
	ds_read_b64_tr_b16 v[126:127], v220 offset:45056
	ds_read_b64_tr_b16 v[128:129], v220 offset:53248
	v_mfma_f32_16x16x32_bf16 v[70:73], v[140:143], v[108:111], v[72:75]
	ds_read_b64_tr_b16 v[130:131], v220 offset:61440
	v_mfma_f32_16x16x32_bf16 v[80:83], v[132:135], v[100:103], v[80:83]
	ds_read_b64_tr_b16 v[132:133], v171 offset:36864
	ds_read_b64_tr_b16 v[134:135], v171 offset:45056
	ds_read_b64_tr_b16 v[136:137], v171 offset:53248
	v_mfma_f32_16x16x32_bf16 v[72:75], v[144:147], v[100:103], v[70:73]
	ds_read_b64_tr_b16 v[138:139], v171 offset:61440
	s_waitcnt lgkmcnt(0)
	v_mfma_f32_16x16x32_bf16 v[56:59], v[104:107], v[108:111], v[56:59]
	ds_read_b64_tr_b16 v[104:105], v172 offset:37120
	ds_read_b64_tr_b16 v[106:107], v172 offset:45312
	v_mfma_f32_16x16x32_bf16 v[48:51], v[116:119], v[108:111], v[48:51]
	v_mfma_f32_16x16x32_bf16 v[56:59], v[112:115], v[100:103], v[56:59]
	ds_read_b64_tr_b16 v[112:113], v172 offset:53504
	ds_read_b64_tr_b16 v[114:115], v172 offset:61696
	ds_read_b64_tr_b16 v[116:117], v175 offset:37120
	ds_read_b64_tr_b16 v[118:119], v175 offset:45312
	v_mfma_f32_16x16x32_bf16 v[40:43], v[124:127], v[108:111], v[40:43]
	v_mfma_f32_16x16x32_bf16 v[48:51], v[120:123], v[100:103], v[48:51]
	ds_read_b64_tr_b16 v[120:121], v175 offset:53504
	ds_read_b64_tr_b16 v[122:123], v175 offset:61696
	ds_read_b64_tr_b16 v[124:125], v176 offset:37120
	ds_read_b64_tr_b16 v[126:127], v176 offset:45312
	v_mfma_f32_16x16x32_bf16 v[32:35], v[132:135], v[108:111], v[32:35]
	v_mfma_f32_16x16x32_bf16 v[40:43], v[128:131], v[100:103], v[40:43]
	ds_read_b64_tr_b16 v[128:129], v176 offset:53504
	ds_read_b64_tr_b16 v[130:131], v176 offset:61696
	ds_read_b64_tr_b16 v[132:133], v181 offset:37120
	ds_read_b64_tr_b16 v[134:135], v181 offset:45312
	v_mfma_f32_16x16x32_bf16 v[32:35], v[136:139], v[100:103], v[32:35]
	ds_read_b64_tr_b16 v[136:137], v181 offset:53504
	ds_read_b64_tr_b16 v[138:139], v181 offset:61696
	s_waitcnt lgkmcnt(0)
	v_mfma_f32_16x16x32_bf16 v[92:95], v[104:107], v[108:111], v[92:95]
	ds_read_b64_tr_b16 v[104:105], v218 offset:37120
	ds_read_b64_tr_b16 v[106:107], v218 offset:45312
	v_mfma_f32_16x16x32_bf16 v[84:87], v[116:119], v[108:111], v[84:87]
	v_mfma_f32_16x16x32_bf16 v[92:95], v[112:115], v[100:103], v[92:95]
	ds_read_b64_tr_b16 v[112:113], v218 offset:53504
	ds_read_b64_tr_b16 v[114:115], v218 offset:61696
	ds_read_b64_tr_b16 v[116:117], v219 offset:37120
	ds_read_b64_tr_b16 v[118:119], v219 offset:45312
	v_mfma_f32_16x16x32_bf16 v[76:79], v[124:127], v[108:111], v[76:79]
	v_mfma_f32_16x16x32_bf16 v[84:87], v[120:123], v[100:103], v[84:87]
	ds_read_b64_tr_b16 v[120:121], v219 offset:53504
	ds_read_b64_tr_b16 v[122:123], v219 offset:61696
	ds_read_b64_tr_b16 v[124:125], v220 offset:37120
	ds_read_b64_tr_b16 v[126:127], v220 offset:45312
	v_mfma_f32_16x16x32_bf16 v[66:69], v[132:135], v[108:111], v[66:69]
	v_mfma_f32_16x16x32_bf16 v[76:79], v[128:131], v[100:103], v[76:79]
	ds_read_b64_tr_b16 v[128:129], v220 offset:53504
	ds_read_b64_tr_b16 v[130:131], v220 offset:61696
	ds_read_b64_tr_b16 v[132:133], v171 offset:37120
	ds_read_b64_tr_b16 v[134:135], v171 offset:45312
	v_mfma_f32_16x16x32_bf16 v[68:71], v[136:139], v[100:103], v[66:69]
	ds_read_b64_tr_b16 v[136:137], v171 offset:53504
	ds_read_b64_tr_b16 v[138:139], v171 offset:61696
	s_waitcnt lgkmcnt(0)
	v_mfma_f32_16x16x32_bf16 v[60:63], v[104:107], v[108:111], v[60:63]
	s_waitcnt vmcnt(6)
	ds_write_b128 v166, v[24:27]
	v_mfma_f32_16x16x32_bf16 v[52:55], v[116:119], v[108:111], v[52:55]
	ds_write_b128 v167, v[28:31]
	v_mfma_f32_16x16x32_bf16 v[44:47], v[124:127], v[108:111], v[44:47]
	ds_write_b128 v169, v[206:209] offset:0
	v_mfma_f32_16x16x32_bf16 v[36:39], v[132:135], v[108:111], v[36:39]
	ds_write_b128 v169, v[210:213] offset:8192
	v_mfma_f32_16x16x32_bf16 v[60:63], v[112:115], v[100:103], v[60:63]
	ds_write_b128 v169, v[214:217] offset:16384
	v_mfma_f32_16x16x32_bf16 v[52:55], v[120:123], v[100:103], v[52:55]
	ds_write_b128 v169, v[248:251] offset:24576
	v_mfma_f32_16x16x32_bf16 v[44:47], v[128:131], v[100:103], v[44:47]
	v_mfma_f32_16x16x32_bf16 v[36:39], v[136:139], v[100:103], v[36:39]
	v_add_f32_e32 v24, v153, v152
	v_add_f32_e32 v24, v223, v24
	v_add_f32_e32 v24, v224, v24
	v_add_f32_e32 v66, v225, v24
	s_waitcnt lgkmcnt(0)
	s_barrier
	s_lshl_b32 s0, s0, 6
	s_addk_i32 s0, 0xc0
	s_mul_i32 s29, s0, 0xa080
	s_add_u32 s72, s24, s29
	s_addc_u32 s73, s25, 0
	s_add_u32 s74, s26, s29
	s_addc_u32 s75, s27, 0
	s_add_u32 s76, s74, 0xa0800
	s_addc_u32 s77, s75, 0
	s_add_u32 s78, s76, 0xa0800
	s_addc_u32 s79, s77, 0
	s_add_u32 s80, s78, 0xa0800
	s_addc_u32 s81, s79, 0
	s_addk_i32 s17, 0x80
	s_cmp_lt_u32 s8, 30
	v_add_f32_e32 v222, v222, v66
	s_cbranch_scc0 .LBB0_248
	s_mov_b32 s0, s8
	s_branch .LBB0_252
